# saddr K-loop: pointer-advance SALU moved from the loop tail into m0 wait-state slots of the last load segment
# baseline (speedup 1.0000x reference)
.Lprio_done:
	s_add_u32 s0, s90, 0x80
	s_addc_u32 s1, s91, 0
	s_add_u32 s11, s2, 0x100
	s_addc_u32 s24, s3, 0
	s_mov_b32 s2, 0
	s_add_i32 s90, s2, 2
	s_add_u32 s82, s0, 0x80
	s_addc_u32 s3, s1, 0
	s_add_i32 s83, 0, 0x10000
	s_cmp_eq_u32 s62, s2
	s_cselect_b32 s3, s23, s3
	s_cselect_b32 s2, s22, s82
	s_cselect_b32 vcc_hi, s13, s24
	s_cselect_b32 vcc_lo, s12, s11
	s_add_i32 s82, 0, 0x14000
	v_add_u32_e32 v140, s83, v157
	v_add_u32_e32 v144, s82, v157
	v_add_u32_e32 v232, s26, v150
	v_add_u32_e32 v233, s26, v154
	v_add_u32_e32 v234, s58, v148
	v_add_u32_e32 v235, s58, v152
	ds_read_b128 v[128:131], v140
	ds_read_b128 v[132:135], v140 offset:1024
	ds_read_b128 v[136:139], v140 offset:2048
	ds_read_b128 v[140:143], v140 offset:3072
	ds_read_b128 v[166:169], v144
	ds_read_b128 v[176:179], v144 offset:1024
	ds_read_b128 v[180:183], v144 offset:2048
	ds_read_b128 v[184:187], v144 offset:3072
	s_add_i32 m0, s37, 0xc000
	ds_read_b128 v[188:191], v242
	ds_read_b128 v[192:195], v242 offset:1024
	ds_read_b128 v[196:199], v242 offset:2048
	ds_read_b128 v[200:203], v242 offset:3072
	ds_read_b128 v[204:207], v242 offset:4096
	ds_read_b128 v[208:211], v242 offset:5120
	ds_read_b128 v[212:215], v242 offset:6144
	ds_read_b128 v[216:219], v242 offset:7168
	global_load_lds_dwordx4 v160, s[0:1]
	s_add_i32 m0, s37, 0xe000
	s_nop 0
	global_load_lds_dwordx4 v162, s[0:1]
	s_waitcnt vmcnt(8) lgkmcnt(0)
	s_barrier
	v_mfma_f32_16x16x32_bf16 v[124:127], v[128:131], v[188:191], 0
	v_mfma_f32_16x16x32_bf16 v[120:123], v[136:139], v[188:191], 0
	v_mfma_f32_16x16x32_bf16 v[108:111], v[128:131], v[196:199], 0
	v_mfma_f32_16x16x32_bf16 v[104:107], v[136:139], v[196:199], 0
	v_mfma_f32_16x16x32_bf16 v[92:95], v[128:131], v[204:207], 0
	v_mfma_f32_16x16x32_bf16 v[88:91], v[136:139], v[204:207], 0
	v_mfma_f32_16x16x32_bf16 v[76:79], v[128:131], v[212:215], 0
	v_mfma_f32_16x16x32_bf16 v[72:75], v[136:139], v[212:215], 0
	v_mfma_f32_16x16x32_bf16 v[124:127], v[132:135], v[192:195], v[124:127]
	v_mfma_f32_16x16x32_bf16 v[120:123], v[140:143], v[192:195], v[120:123]
	v_mfma_f32_16x16x32_bf16 v[108:111], v[132:135], v[200:203], v[108:111]
	v_mfma_f32_16x16x32_bf16 v[104:107], v[140:143], v[200:203], v[104:107]
	v_mfma_f32_16x16x32_bf16 v[92:95], v[132:135], v[208:211], v[92:95]
	v_mfma_f32_16x16x32_bf16 v[88:91], v[140:143], v[208:211], v[88:91]
	v_mfma_f32_16x16x32_bf16 v[76:79], v[132:135], v[216:219], v[76:79]
	v_mfma_f32_16x16x32_bf16 v[72:75], v[140:143], v[216:219], v[72:75]
	v_mfma_f32_16x16x32_bf16 v[116:119], v[166:169], v[188:191], 0
	v_mfma_f32_16x16x32_bf16 v[112:115], v[180:183], v[188:191], 0
	v_mfma_f32_16x16x32_bf16 v[100:103], v[166:169], v[196:199], 0
	v_mfma_f32_16x16x32_bf16 v[96:99], v[180:183], v[196:199], 0
	v_mfma_f32_16x16x32_bf16 v[84:87], v[166:169], v[204:207], 0
	v_mfma_f32_16x16x32_bf16 v[80:83], v[180:183], v[204:207], 0
	v_mfma_f32_16x16x32_bf16 v[68:71], v[166:169], v[212:215], 0
	v_mfma_f32_16x16x32_bf16 v[64:67], v[180:183], v[212:215], 0
	v_mfma_f32_16x16x32_bf16 v[116:119], v[176:179], v[192:195], v[116:119]
	v_mfma_f32_16x16x32_bf16 v[112:115], v[184:187], v[192:195], v[112:115]
	v_mfma_f32_16x16x32_bf16 v[100:103], v[176:179], v[200:203], v[100:103]
	v_mfma_f32_16x16x32_bf16 v[96:99], v[184:187], v[200:203], v[96:99]
	v_mfma_f32_16x16x32_bf16 v[84:87], v[176:179], v[208:211], v[84:87]
	v_mfma_f32_16x16x32_bf16 v[80:83], v[184:187], v[208:211], v[80:83]
	v_mfma_f32_16x16x32_bf16 v[68:71], v[176:179], v[216:219], v[68:71]
	v_mfma_f32_16x16x32_bf16 v[64:67], v[184:187], v[216:219], v[64:67]
	s_barrier
	s_add_i32 s83, s83, s36
	s_mov_b32 m0, s83
	ds_read_b128 v[188:191], v242 offset:16384
	ds_read_b128 v[192:195], v242 offset:17408
	ds_read_b128 v[196:199], v242 offset:18432
	ds_read_b128 v[200:203], v242 offset:19456
	ds_read_b128 v[204:207], v242 offset:20480
	ds_read_b128 v[208:211], v242 offset:21504
	ds_read_b128 v[212:215], v242 offset:22528
	ds_read_b128 v[216:219], v242 offset:23552
	global_load_lds_dwordx4 v150, vcc
	s_add_i32 m0, s83, 0x2000
	s_add_i32 s82, s82, s36
	global_load_lds_dwordx4 v154, vcc
	s_mov_b32 m0, s82
	s_nop 0
	global_load_lds_dwordx4 v232, vcc
	s_add_i32 m0, s82, 0x2000
	s_nop 0
	global_load_lds_dwordx4 v233, vcc
	s_mov_b32 m0, s37
	s_nop 0
	global_load_lds_dwordx4 v148, s[2:3]
	s_mov_b32 m0, s42
	s_nop 0
	global_load_lds_dwordx4 v152, s[2:3]
	s_waitcnt vmcnt(8) lgkmcnt(0)
	s_barrier
	v_mfma_f32_16x16x32_bf16 v[60:63], v[128:131], v[188:191], 0
	v_mfma_f32_16x16x32_bf16 v[56:59], v[136:139], v[188:191], 0
	v_mfma_f32_16x16x32_bf16 v[44:47], v[128:131], v[196:199], 0
	v_mfma_f32_16x16x32_bf16 v[40:43], v[136:139], v[196:199], 0
	v_mfma_f32_16x16x32_bf16 v[28:31], v[128:131], v[204:207], 0
	v_mfma_f32_16x16x32_bf16 v[24:27], v[136:139], v[204:207], 0
	v_mfma_f32_16x16x32_bf16 v[12:15], v[128:131], v[212:215], 0
	v_mfma_f32_16x16x32_bf16 v[8:11], v[136:139], v[212:215], 0
	v_mfma_f32_16x16x32_bf16 v[60:63], v[132:135], v[192:195], v[60:63]
	v_mfma_f32_16x16x32_bf16 v[56:59], v[140:143], v[192:195], v[56:59]
	v_mfma_f32_16x16x32_bf16 v[44:47], v[132:135], v[200:203], v[44:47]
	v_mfma_f32_16x16x32_bf16 v[40:43], v[140:143], v[200:203], v[40:43]
	v_mfma_f32_16x16x32_bf16 v[28:31], v[132:135], v[208:211], v[28:31]
	v_mfma_f32_16x16x32_bf16 v[24:27], v[140:143], v[208:211], v[24:27]
	v_mfma_f32_16x16x32_bf16 v[12:15], v[132:135], v[216:219], v[12:15]
	v_mfma_f32_16x16x32_bf16 v[8:11], v[140:143], v[216:219], v[8:11]
	v_mfma_f32_16x16x32_bf16 v[52:55], v[166:169], v[188:191], 0
	v_mfma_f32_16x16x32_bf16 v[48:51], v[180:183], v[188:191], 0
	v_mfma_f32_16x16x32_bf16 v[36:39], v[166:169], v[196:199], 0
	v_mfma_f32_16x16x32_bf16 v[32:35], v[180:183], v[196:199], 0
	v_mfma_f32_16x16x32_bf16 v[20:23], v[166:169], v[204:207], 0
	v_mfma_f32_16x16x32_bf16 v[16:19], v[180:183], v[204:207], 0
	v_mfma_f32_16x16x32_bf16 v[4:7], v[166:169], v[212:215], 0
	v_mfma_f32_16x16x32_bf16 v[0:3], v[180:183], v[212:215], 0
	v_mfma_f32_16x16x32_bf16 v[52:55], v[176:179], v[192:195], v[52:55]
	v_mfma_f32_16x16x32_bf16 v[48:51], v[184:187], v[192:195], v[48:51]
	v_mfma_f32_16x16x32_bf16 v[36:39], v[176:179], v[200:203], v[36:39]
	v_mfma_f32_16x16x32_bf16 v[32:35], v[184:187], v[200:203], v[32:35]
	v_mfma_f32_16x16x32_bf16 v[20:23], v[176:179], v[208:211], v[20:23]
	v_mfma_f32_16x16x32_bf16 v[16:19], v[184:187], v[208:211], v[16:19]
	v_mfma_f32_16x16x32_bf16 v[4:7], v[176:179], v[216:219], v[4:7]
	v_mfma_f32_16x16x32_bf16 v[0:3], v[184:187], v[216:219], v[0:3]
	s_barrier
	s_add_i32 s82, 0, 0x18000
	s_add_i32 s83, 0, 0x1c000
	v_add_u32_e32 v140, s82, v157
	v_add_u32_e32 v144, s83, v157
	ds_read_b128 v[128:131], v140
	ds_read_b128 v[132:135], v140 offset:1024
	ds_read_b128 v[136:139], v140 offset:2048
	ds_read_b128 v[140:143], v140 offset:3072
	ds_read_b128 v[166:169], v144
	ds_read_b128 v[176:179], v144 offset:1024
	ds_read_b128 v[180:183], v144 offset:2048
	ds_read_b128 v[184:187], v144 offset:3072
	s_mov_b32 m0, s43
	ds_read_b128 v[188:191], v242 offset:32768
	ds_read_b128 v[192:195], v242 offset:33792
	ds_read_b128 v[196:199], v242 offset:34816
	ds_read_b128 v[200:203], v242 offset:35840
	ds_read_b128 v[204:207], v242 offset:36864
	ds_read_b128 v[208:211], v242 offset:37888
	ds_read_b128 v[212:215], v242 offset:38912
	ds_read_b128 v[216:219], v242 offset:39936
	global_load_lds_dwordx4 v234, s[2:3]
	s_mov_b32 m0, s16
	s_nop 0
	global_load_lds_dwordx4 v235, s[2:3]
	s_waitcnt vmcnt(8) lgkmcnt(0)
	s_barrier
	v_mfma_f32_16x16x32_bf16 v[124:127], v[128:131], v[188:191], v[124:127]
	v_mfma_f32_16x16x32_bf16 v[120:123], v[136:139], v[188:191], v[120:123]
	v_mfma_f32_16x16x32_bf16 v[108:111], v[128:131], v[196:199], v[108:111]
	v_mfma_f32_16x16x32_bf16 v[104:107], v[136:139], v[196:199], v[104:107]
	v_mfma_f32_16x16x32_bf16 v[92:95], v[128:131], v[204:207], v[92:95]
	v_mfma_f32_16x16x32_bf16 v[88:91], v[136:139], v[204:207], v[88:91]
	v_mfma_f32_16x16x32_bf16 v[76:79], v[128:131], v[212:215], v[76:79]
	v_mfma_f32_16x16x32_bf16 v[72:75], v[136:139], v[212:215], v[72:75]
	v_mfma_f32_16x16x32_bf16 v[124:127], v[132:135], v[192:195], v[124:127]
	v_mfma_f32_16x16x32_bf16 v[120:123], v[140:143], v[192:195], v[120:123]
	v_mfma_f32_16x16x32_bf16 v[108:111], v[132:135], v[200:203], v[108:111]
	v_mfma_f32_16x16x32_bf16 v[104:107], v[140:143], v[200:203], v[104:107]
	v_mfma_f32_16x16x32_bf16 v[92:95], v[132:135], v[208:211], v[92:95]
	v_mfma_f32_16x16x32_bf16 v[88:91], v[140:143], v[208:211], v[88:91]
	v_mfma_f32_16x16x32_bf16 v[76:79], v[132:135], v[216:219], v[76:79]
	v_mfma_f32_16x16x32_bf16 v[72:75], v[140:143], v[216:219], v[72:75]
	v_mfma_f32_16x16x32_bf16 v[116:119], v[166:169], v[188:191], v[116:119]
	v_mfma_f32_16x16x32_bf16 v[112:115], v[180:183], v[188:191], v[112:115]
	v_mfma_f32_16x16x32_bf16 v[100:103], v[166:169], v[196:199], v[100:103]
	v_mfma_f32_16x16x32_bf16 v[96:99], v[180:183], v[196:199], v[96:99]
	v_mfma_f32_16x16x32_bf16 v[84:87], v[166:169], v[204:207], v[84:87]
	v_mfma_f32_16x16x32_bf16 v[80:83], v[180:183], v[204:207], v[80:83]
	v_mfma_f32_16x16x32_bf16 v[68:71], v[166:169], v[212:215], v[68:71]
	v_mfma_f32_16x16x32_bf16 v[64:67], v[180:183], v[212:215], v[64:67]
	v_mfma_f32_16x16x32_bf16 v[116:119], v[176:179], v[192:195], v[116:119]
	v_mfma_f32_16x16x32_bf16 v[112:115], v[184:187], v[192:195], v[112:115]
	v_mfma_f32_16x16x32_bf16 v[100:103], v[176:179], v[200:203], v[100:103]
	v_mfma_f32_16x16x32_bf16 v[96:99], v[184:187], v[200:203], v[96:99]
	v_mfma_f32_16x16x32_bf16 v[84:87], v[176:179], v[208:211], v[84:87]
	v_mfma_f32_16x16x32_bf16 v[80:83], v[184:187], v[208:211], v[80:83]
	v_mfma_f32_16x16x32_bf16 v[68:71], v[176:179], v[216:219], v[68:71]
	v_mfma_f32_16x16x32_bf16 v[64:67], v[184:187], v[216:219], v[64:67]
	s_barrier
	s_add_i32 m0, s82, s36
	ds_read_b128 v[188:191], v242 offset:49152
	ds_read_b128 v[192:195], v242 offset:50176
	ds_read_b128 v[196:199], v242 offset:51200
	ds_read_b128 v[200:203], v242 offset:52224
	ds_read_b128 v[204:207], v242 offset:53248
	ds_read_b128 v[208:211], v242 offset:54272
	ds_read_b128 v[212:215], v242 offset:55296
	ds_read_b128 v[216:219], v242 offset:56320
	s_add_u32 vcc_lo, vcc_lo, 0x80
	s_addc_u32 vcc_hi, vcc_hi, 0
	global_load_lds_dwordx4 v150, vcc
	s_add_i32 m0, m0, 0x2000
	s_add_u32 s2, s2, 0x80
	s_addc_u32 s3, s3, 0
	global_load_lds_dwordx4 v154, vcc
	s_add_i32 m0, s83, s36
	s_nop 0
	global_load_lds_dwordx4 v232, vcc
	s_add_i32 m0, m0, 0x2000
	s_add_u32 s0, s0, 0x100
	s_addc_u32 s1, s1, 0
	global_load_lds_dwordx4 v233, vcc
	s_mov_b32 m0, s63
	s_add_u32 s11, s11, 0x100
	s_addc_u32 s24, s24, 0
	global_load_lds_dwordx4 v148, s[2:3]
	s_mov_b32 m0, s18
	s_nop 0
	global_load_lds_dwordx4 v152, s[2:3]
	s_waitcnt vmcnt(8) lgkmcnt(0)
	s_barrier
	v_mfma_f32_16x16x32_bf16 v[60:63], v[128:131], v[188:191], v[60:63]
	v_mfma_f32_16x16x32_bf16 v[56:59], v[136:139], v[188:191], v[56:59]
	v_mfma_f32_16x16x32_bf16 v[44:47], v[128:131], v[196:199], v[44:47]
	v_mfma_f32_16x16x32_bf16 v[40:43], v[136:139], v[196:199], v[40:43]
	v_mfma_f32_16x16x32_bf16 v[28:31], v[128:131], v[204:207], v[28:31]
	v_mfma_f32_16x16x32_bf16 v[24:27], v[136:139], v[204:207], v[24:27]
	v_mfma_f32_16x16x32_bf16 v[12:15], v[128:131], v[212:215], v[12:15]
	v_mfma_f32_16x16x32_bf16 v[8:11], v[136:139], v[212:215], v[8:11]
	v_mfma_f32_16x16x32_bf16 v[60:63], v[132:135], v[192:195], v[60:63]
	v_mfma_f32_16x16x32_bf16 v[56:59], v[140:143], v[192:195], v[56:59]
	v_mfma_f32_16x16x32_bf16 v[44:47], v[132:135], v[200:203], v[44:47]
	v_mfma_f32_16x16x32_bf16 v[40:43], v[140:143], v[200:203], v[40:43]
	v_mfma_f32_16x16x32_bf16 v[28:31], v[132:135], v[208:211], v[28:31]
	v_mfma_f32_16x16x32_bf16 v[24:27], v[140:143], v[208:211], v[24:27]
	v_mfma_f32_16x16x32_bf16 v[12:15], v[132:135], v[216:219], v[12:15]
	v_mfma_f32_16x16x32_bf16 v[8:11], v[140:143], v[216:219], v[8:11]
	v_mfma_f32_16x16x32_bf16 v[52:55], v[166:169], v[188:191], v[52:55]
	v_mfma_f32_16x16x32_bf16 v[48:51], v[180:183], v[188:191], v[48:51]
	v_mfma_f32_16x16x32_bf16 v[36:39], v[166:169], v[196:199], v[36:39]
	v_mfma_f32_16x16x32_bf16 v[32:35], v[180:183], v[196:199], v[32:35]
	v_mfma_f32_16x16x32_bf16 v[20:23], v[166:169], v[204:207], v[20:23]
	v_mfma_f32_16x16x32_bf16 v[16:19], v[180:183], v[204:207], v[16:19]
	v_mfma_f32_16x16x32_bf16 v[4:7], v[166:169], v[212:215], v[4:7]
	v_mfma_f32_16x16x32_bf16 v[0:3], v[180:183], v[212:215], v[0:3]
	v_mfma_f32_16x16x32_bf16 v[52:55], v[176:179], v[192:195], v[52:55]
	v_mfma_f32_16x16x32_bf16 v[48:51], v[184:187], v[192:195], v[48:51]
	v_mfma_f32_16x16x32_bf16 v[36:39], v[176:179], v[200:203], v[36:39]
	v_mfma_f32_16x16x32_bf16 v[32:35], v[184:187], v[200:203], v[32:35]
	v_mfma_f32_16x16x32_bf16 v[20:23], v[176:179], v[208:211], v[20:23]
	v_mfma_f32_16x16x32_bf16 v[16:19], v[184:187], v[208:211], v[16:19]
	v_mfma_f32_16x16x32_bf16 v[4:7], v[176:179], v[216:219], v[4:7]
	v_mfma_f32_16x16x32_bf16 v[0:3], v[184:187], v[216:219], v[0:3]
	s_barrier
	s_cmp_ge_u32 s90, s60
	s_mov_b32 s2, s90
	s_cbranch_scc1 .LBB0_297
.LBB0_295:
	s_add_i32 s90, s2, 2
	s_add_u32 s82, s0, 0x80
	s_addc_u32 s3, s1, 0
	s_add_i32 s83, 0, 0x10000
	s_cmp_eq_u32 s62, s2
	s_cselect_b32 s3, s23, s3
	s_cselect_b32 s2, s22, s82
	s_cselect_b32 vcc_hi, s13, s24
	s_cselect_b32 vcc_lo, s12, s11
	s_add_i32 s82, 0, 0x14000
	v_add_u32_e32 v140, s83, v157
	v_add_u32_e32 v144, s82, v157
	ds_read_b128 v[128:131], v140
	ds_read_b128 v[132:135], v140 offset:1024
	ds_read_b128 v[136:139], v140 offset:2048
	ds_read_b128 v[140:143], v140 offset:3072
	ds_read_b128 v[166:169], v144
	ds_read_b128 v[176:179], v144 offset:1024
	ds_read_b128 v[180:183], v144 offset:2048
	ds_read_b128 v[184:187], v144 offset:3072
	s_add_i32 m0, s37, 0xc000
	ds_read_b128 v[188:191], v242
	ds_read_b128 v[192:195], v242 offset:1024
	ds_read_b128 v[196:199], v242 offset:2048
	ds_read_b128 v[200:203], v242 offset:3072
	ds_read_b128 v[204:207], v242 offset:4096
	ds_read_b128 v[208:211], v242 offset:5120
	ds_read_b128 v[212:215], v242 offset:6144
	ds_read_b128 v[216:219], v242 offset:7168
	global_load_lds_dwordx4 v160, s[0:1]
	s_add_i32 m0, s37, 0xe000
	s_nop 0
	global_load_lds_dwordx4 v162, s[0:1]
	s_waitcnt vmcnt(8) lgkmcnt(0)
	s_barrier
	v_mfma_f32_16x16x32_bf16 v[124:127], v[128:131], v[188:191], v[124:127]
	v_mfma_f32_16x16x32_bf16 v[120:123], v[136:139], v[188:191], v[120:123]
	v_mfma_f32_16x16x32_bf16 v[108:111], v[128:131], v[196:199], v[108:111]
	v_mfma_f32_16x16x32_bf16 v[104:107], v[136:139], v[196:199], v[104:107]
	v_mfma_f32_16x16x32_bf16 v[92:95], v[128:131], v[204:207], v[92:95]
	v_mfma_f32_16x16x32_bf16 v[88:91], v[136:139], v[204:207], v[88:91]
	v_mfma_f32_16x16x32_bf16 v[76:79], v[128:131], v[212:215], v[76:79]
	v_mfma_f32_16x16x32_bf16 v[72:75], v[136:139], v[212:215], v[72:75]
	v_mfma_f32_16x16x32_bf16 v[124:127], v[132:135], v[192:195], v[124:127]
	v_mfma_f32_16x16x32_bf16 v[120:123], v[140:143], v[192:195], v[120:123]
	v_mfma_f32_16x16x32_bf16 v[108:111], v[132:135], v[200:203], v[108:111]
	v_mfma_f32_16x16x32_bf16 v[104:107], v[140:143], v[200:203], v[104:107]
	v_mfma_f32_16x16x32_bf16 v[92:95], v[132:135], v[208:211], v[92:95]
	v_mfma_f32_16x16x32_bf16 v[88:91], v[140:143], v[208:211], v[88:91]
	v_mfma_f32_16x16x32_bf16 v[76:79], v[132:135], v[216:219], v[76:79]
	v_mfma_f32_16x16x32_bf16 v[72:75], v[140:143], v[216:219], v[72:75]
	v_mfma_f32_16x16x32_bf16 v[116:119], v[166:169], v[188:191], v[116:119]
	v_mfma_f32_16x16x32_bf16 v[112:115], v[180:183], v[188:191], v[112:115]
	v_mfma_f32_16x16x32_bf16 v[100:103], v[166:169], v[196:199], v[100:103]
	v_mfma_f32_16x16x32_bf16 v[96:99], v[180:183], v[196:199], v[96:99]
	v_mfma_f32_16x16x32_bf16 v[84:87], v[166:169], v[204:207], v[84:87]
	v_mfma_f32_16x16x32_bf16 v[80:83], v[180:183], v[204:207], v[80:83]
	v_mfma_f32_16x16x32_bf16 v[68:71], v[166:169], v[212:215], v[68:71]
	v_mfma_f32_16x16x32_bf16 v[64:67], v[180:183], v[212:215], v[64:67]
	v_mfma_f32_16x16x32_bf16 v[116:119], v[176:179], v[192:195], v[116:119]
	v_mfma_f32_16x16x32_bf16 v[112:115], v[184:187], v[192:195], v[112:115]
	v_mfma_f32_16x16x32_bf16 v[100:103], v[176:179], v[200:203], v[100:103]
	v_mfma_f32_16x16x32_bf16 v[96:99], v[184:187], v[200:203], v[96:99]
	v_mfma_f32_16x16x32_bf16 v[84:87], v[176:179], v[208:211], v[84:87]
	v_mfma_f32_16x16x32_bf16 v[80:83], v[184:187], v[208:211], v[80:83]
	v_mfma_f32_16x16x32_bf16 v[68:71], v[176:179], v[216:219], v[68:71]
	v_mfma_f32_16x16x32_bf16 v[64:67], v[184:187], v[216:219], v[64:67]
	s_barrier
	s_add_i32 s83, s83, s36
	s_mov_b32 m0, s83
	ds_read_b128 v[188:191], v242 offset:16384
	ds_read_b128 v[192:195], v242 offset:17408
	ds_read_b128 v[196:199], v242 offset:18432
	ds_read_b128 v[200:203], v242 offset:19456
	ds_read_b128 v[204:207], v242 offset:20480
	ds_read_b128 v[208:211], v242 offset:21504
	ds_read_b128 v[212:215], v242 offset:22528
	ds_read_b128 v[216:219], v242 offset:23552
	global_load_lds_dwordx4 v150, vcc
	s_add_i32 m0, s83, 0x2000
	s_add_i32 s82, s82, s36
	global_load_lds_dwordx4 v154, vcc
	s_mov_b32 m0, s82
	s_nop 0
	global_load_lds_dwordx4 v232, vcc
	s_add_i32 m0, s82, 0x2000
	s_nop 0
	global_load_lds_dwordx4 v233, vcc
	s_mov_b32 m0, s37
	s_nop 0
	global_load_lds_dwordx4 v148, s[2:3]
	s_mov_b32 m0, s42
	s_nop 0
	global_load_lds_dwordx4 v152, s[2:3]
	s_waitcnt vmcnt(8) lgkmcnt(0)
	s_barrier
	v_mfma_f32_16x16x32_bf16 v[60:63], v[128:131], v[188:191], v[60:63]
	v_mfma_f32_16x16x32_bf16 v[56:59], v[136:139], v[188:191], v[56:59]
	v_mfma_f32_16x16x32_bf16 v[44:47], v[128:131], v[196:199], v[44:47]
	v_mfma_f32_16x16x32_bf16 v[40:43], v[136:139], v[196:199], v[40:43]
	v_mfma_f32_16x16x32_bf16 v[28:31], v[128:131], v[204:207], v[28:31]
	v_mfma_f32_16x16x32_bf16 v[24:27], v[136:139], v[204:207], v[24:27]
	v_mfma_f32_16x16x32_bf16 v[12:15], v[128:131], v[212:215], v[12:15]
	v_mfma_f32_16x16x32_bf16 v[8:11], v[136:139], v[212:215], v[8:11]
	v_mfma_f32_16x16x32_bf16 v[60:63], v[132:135], v[192:195], v[60:63]
	v_mfma_f32_16x16x32_bf16 v[56:59], v[140:143], v[192:195], v[56:59]
	v_mfma_f32_16x16x32_bf16 v[44:47], v[132:135], v[200:203], v[44:47]
	v_mfma_f32_16x16x32_bf16 v[40:43], v[140:143], v[200:203], v[40:43]
	v_mfma_f32_16x16x32_bf16 v[28:31], v[132:135], v[208:211], v[28:31]
	v_mfma_f32_16x16x32_bf16 v[24:27], v[140:143], v[208:211], v[24:27]
	v_mfma_f32_16x16x32_bf16 v[12:15], v[132:135], v[216:219], v[12:15]
	v_mfma_f32_16x16x32_bf16 v[8:11], v[140:143], v[216:219], v[8:11]
	v_mfma_f32_16x16x32_bf16 v[52:55], v[166:169], v[188:191], v[52:55]
	v_mfma_f32_16x16x32_bf16 v[48:51], v[180:183], v[188:191], v[48:51]
	v_mfma_f32_16x16x32_bf16 v[36:39], v[166:169], v[196:199], v[36:39]
	v_mfma_f32_16x16x32_bf16 v[32:35], v[180:183], v[196:199], v[32:35]
	v_mfma_f32_16x16x32_bf16 v[20:23], v[166:169], v[204:207], v[20:23]
	v_mfma_f32_16x16x32_bf16 v[16:19], v[180:183], v[204:207], v[16:19]
	v_mfma_f32_16x16x32_bf16 v[4:7], v[166:169], v[212:215], v[4:7]
	v_mfma_f32_16x16x32_bf16 v[0:3], v[180:183], v[212:215], v[0:3]
	v_mfma_f32_16x16x32_bf16 v[52:55], v[176:179], v[192:195], v[52:55]
	v_mfma_f32_16x16x32_bf16 v[48:51], v[184:187], v[192:195], v[48:51]
	v_mfma_f32_16x16x32_bf16 v[36:39], v[176:179], v[200:203], v[36:39]
	v_mfma_f32_16x16x32_bf16 v[32:35], v[184:187], v[200:203], v[32:35]
	v_mfma_f32_16x16x32_bf16 v[20:23], v[176:179], v[208:211], v[20:23]
	v_mfma_f32_16x16x32_bf16 v[16:19], v[184:187], v[208:211], v[16:19]
	v_mfma_f32_16x16x32_bf16 v[4:7], v[176:179], v[216:219], v[4:7]
	v_mfma_f32_16x16x32_bf16 v[0:3], v[184:187], v[216:219], v[0:3]
	s_barrier
	s_add_i32 s82, 0, 0x18000
	s_add_i32 s83, 0, 0x1c000
	v_add_u32_e32 v140, s82, v157
	v_add_u32_e32 v144, s83, v157
	ds_read_b128 v[128:131], v140
	ds_read_b128 v[132:135], v140 offset:1024
	ds_read_b128 v[136:139], v140 offset:2048
	ds_read_b128 v[140:143], v140 offset:3072
	ds_read_b128 v[166:169], v144
	ds_read_b128 v[176:179], v144 offset:1024
	ds_read_b128 v[180:183], v144 offset:2048
	ds_read_b128 v[184:187], v144 offset:3072
	s_mov_b32 m0, s43
	ds_read_b128 v[188:191], v242 offset:32768
	ds_read_b128 v[192:195], v242 offset:33792
	ds_read_b128 v[196:199], v242 offset:34816
	ds_read_b128 v[200:203], v242 offset:35840
	ds_read_b128 v[204:207], v242 offset:36864
	ds_read_b128 v[208:211], v242 offset:37888
	ds_read_b128 v[212:215], v242 offset:38912
	ds_read_b128 v[216:219], v242 offset:39936
	global_load_lds_dwordx4 v234, s[2:3]
	s_mov_b32 m0, s16
	s_nop 0
	global_load_lds_dwordx4 v235, s[2:3]
	s_waitcnt vmcnt(8) lgkmcnt(0)
	s_barrier
	v_mfma_f32_16x16x32_bf16 v[124:127], v[128:131], v[188:191], v[124:127]
	v_mfma_f32_16x16x32_bf16 v[120:123], v[136:139], v[188:191], v[120:123]
	v_mfma_f32_16x16x32_bf16 v[108:111], v[128:131], v[196:199], v[108:111]
	v_mfma_f32_16x16x32_bf16 v[104:107], v[136:139], v[196:199], v[104:107]
	v_mfma_f32_16x16x32_bf16 v[92:95], v[128:131], v[204:207], v[92:95]
	v_mfma_f32_16x16x32_bf16 v[88:91], v[136:139], v[204:207], v[88:91]
	v_mfma_f32_16x16x32_bf16 v[76:79], v[128:131], v[212:215], v[76:79]
	v_mfma_f32_16x16x32_bf16 v[72:75], v[136:139], v[212:215], v[72:75]
	v_mfma_f32_16x16x32_bf16 v[124:127], v[132:135], v[192:195], v[124:127]
	v_mfma_f32_16x16x32_bf16 v[120:123], v[140:143], v[192:195], v[120:123]
	v_mfma_f32_16x16x32_bf16 v[108:111], v[132:135], v[200:203], v[108:111]
	v_mfma_f32_16x16x32_bf16 v[104:107], v[140:143], v[200:203], v[104:107]
	v_mfma_f32_16x16x32_bf16 v[92:95], v[132:135], v[208:211], v[92:95]
	v_mfma_f32_16x16x32_bf16 v[88:91], v[140:143], v[208:211], v[88:91]
	v_mfma_f32_16x16x32_bf16 v[76:79], v[132:135], v[216:219], v[76:79]
	v_mfma_f32_16x16x32_bf16 v[72:75], v[140:143], v[216:219], v[72:75]
	v_mfma_f32_16x16x32_bf16 v[116:119], v[166:169], v[188:191], v[116:119]
	v_mfma_f32_16x16x32_bf16 v[112:115], v[180:183], v[188:191], v[112:115]
	v_mfma_f32_16x16x32_bf16 v[100:103], v[166:169], v[196:199], v[100:103]
	v_mfma_f32_16x16x32_bf16 v[96:99], v[180:183], v[196:199], v[96:99]
	v_mfma_f32_16x16x32_bf16 v[84:87], v[166:169], v[204:207], v[84:87]
	v_mfma_f32_16x16x32_bf16 v[80:83], v[180:183], v[204:207], v[80:83]
	v_mfma_f32_16x16x32_bf16 v[68:71], v[166:169], v[212:215], v[68:71]
	v_mfma_f32_16x16x32_bf16 v[64:67], v[180:183], v[212:215], v[64:67]
	v_mfma_f32_16x16x32_bf16 v[116:119], v[176:179], v[192:195], v[116:119]
	v_mfma_f32_16x16x32_bf16 v[112:115], v[184:187], v[192:195], v[112:115]
	v_mfma_f32_16x16x32_bf16 v[100:103], v[176:179], v[200:203], v[100:103]
	v_mfma_f32_16x16x32_bf16 v[96:99], v[184:187], v[200:203], v[96:99]
	v_mfma_f32_16x16x32_bf16 v[84:87], v[176:179], v[208:211], v[84:87]
	v_mfma_f32_16x16x32_bf16 v[80:83], v[184:187], v[208:211], v[80:83]
	v_mfma_f32_16x16x32_bf16 v[68:71], v[176:179], v[216:219], v[68:71]
	v_mfma_f32_16x16x32_bf16 v[64:67], v[184:187], v[216:219], v[64:67]
	s_barrier
	s_add_i32 m0, s82, s36
	ds_read_b128 v[188:191], v242 offset:49152
	ds_read_b128 v[192:195], v242 offset:50176
	ds_read_b128 v[196:199], v242 offset:51200
	ds_read_b128 v[200:203], v242 offset:52224
	ds_read_b128 v[204:207], v242 offset:53248
	ds_read_b128 v[208:211], v242 offset:54272
	ds_read_b128 v[212:215], v242 offset:55296
	ds_read_b128 v[216:219], v242 offset:56320
	s_add_u32 vcc_lo, vcc_lo, 0x80
	s_addc_u32 vcc_hi, vcc_hi, 0
	global_load_lds_dwordx4 v150, vcc
	s_add_i32 m0, m0, 0x2000
	s_add_u32 s2, s2, 0x80
	s_addc_u32 s3, s3, 0
	global_load_lds_dwordx4 v154, vcc
	s_add_i32 m0, s83, s36
	s_nop 0
	global_load_lds_dwordx4 v232, vcc
	s_add_i32 m0, m0, 0x2000
	s_add_u32 s0, s0, 0x100
	s_addc_u32 s1, s1, 0
	global_load_lds_dwordx4 v233, vcc
	s_mov_b32 m0, s63
	s_add_u32 s11, s11, 0x100
	s_addc_u32 s24, s24, 0
	global_load_lds_dwordx4 v148, s[2:3]
	s_mov_b32 m0, s18
	s_nop 0
	global_load_lds_dwordx4 v152, s[2:3]
	s_waitcnt vmcnt(8) lgkmcnt(0)
	s_barrier
	v_mfma_f32_16x16x32_bf16 v[60:63], v[128:131], v[188:191], v[60:63]
	v_mfma_f32_16x16x32_bf16 v[56:59], v[136:139], v[188:191], v[56:59]
	v_mfma_f32_16x16x32_bf16 v[44:47], v[128:131], v[196:199], v[44:47]
	v_mfma_f32_16x16x32_bf16 v[40:43], v[136:139], v[196:199], v[40:43]
	v_mfma_f32_16x16x32_bf16 v[28:31], v[128:131], v[204:207], v[28:31]
	v_mfma_f32_16x16x32_bf16 v[24:27], v[136:139], v[204:207], v[24:27]
	v_mfma_f32_16x16x32_bf16 v[12:15], v[128:131], v[212:215], v[12:15]
	v_mfma_f32_16x16x32_bf16 v[8:11], v[136:139], v[212:215], v[8:11]
	v_mfma_f32_16x16x32_bf16 v[60:63], v[132:135], v[192:195], v[60:63]
	v_mfma_f32_16x16x32_bf16 v[56:59], v[140:143], v[192:195], v[56:59]
	v_mfma_f32_16x16x32_bf16 v[44:47], v[132:135], v[200:203], v[44:47]
	v_mfma_f32_16x16x32_bf16 v[40:43], v[140:143], v[200:203], v[40:43]
	v_mfma_f32_16x16x32_bf16 v[28:31], v[132:135], v[208:211], v[28:31]
	v_mfma_f32_16x16x32_bf16 v[24:27], v[140:143], v[208:211], v[24:27]
	v_mfma_f32_16x16x32_bf16 v[12:15], v[132:135], v[216:219], v[12:15]
	v_mfma_f32_16x16x32_bf16 v[8:11], v[140:143], v[216:219], v[8:11]
	v_mfma_f32_16x16x32_bf16 v[52:55], v[166:169], v[188:191], v[52:55]
	v_mfma_f32_16x16x32_bf16 v[48:51], v[180:183], v[188:191], v[48:51]
	v_mfma_f32_16x16x32_bf16 v[36:39], v[166:169], v[196:199], v[36:39]
	v_mfma_f32_16x16x32_bf16 v[32:35], v[180:183], v[196:199], v[32:35]
	v_mfma_f32_16x16x32_bf16 v[20:23], v[166:169], v[204:207], v[20:23]
	v_mfma_f32_16x16x32_bf16 v[16:19], v[180:183], v[204:207], v[16:19]
	v_mfma_f32_16x16x32_bf16 v[4:7], v[166:169], v[212:215], v[4:7]
	v_mfma_f32_16x16x32_bf16 v[0:3], v[180:183], v[212:215], v[0:3]
	v_mfma_f32_16x16x32_bf16 v[52:55], v[176:179], v[192:195], v[52:55]
	v_mfma_f32_16x16x32_bf16 v[48:51], v[184:187], v[192:195], v[48:51]
	v_mfma_f32_16x16x32_bf16 v[36:39], v[176:179], v[200:203], v[36:39]
	v_mfma_f32_16x16x32_bf16 v[32:35], v[184:187], v[200:203], v[32:35]
	v_mfma_f32_16x16x32_bf16 v[20:23], v[176:179], v[208:211], v[20:23]
	v_mfma_f32_16x16x32_bf16 v[16:19], v[184:187], v[208:211], v[16:19]
	v_mfma_f32_16x16x32_bf16 v[4:7], v[176:179], v[216:219], v[4:7]
	v_mfma_f32_16x16x32_bf16 v[0:3], v[184:187], v[216:219], v[0:3]
	s_barrier
	s_cmp_ge_u32 s90, s60
	s_mov_b32 s2, s90
	s_cbranch_scc0 .LBB0_295
	s_branch .LBB0_297
